# MLA tile loop: static s_setprio 1 around the QK and PV MFMA bursts (MFMA issue wins over the partner wave's softmax VALU)
# speedup vs baseline: 1.0002x; 1.0002x over previous
.LBB0_1374:
	s_and_b32 s99, s27, 1
	s_mul_i32 s99, s99, 0x3800
	v_add_u32_e32 v124, s99, v175
	ds_read_b128 v[76:79], v124
	ds_read_b128 v[88:91], v124 offset:64
	s_and_b32 s0, s27, 1
	s_mul_i32 s1, s0, 0x3800
	s_waitcnt lgkmcnt(1)
	s_setprio 1
	v_mfma_f32_16x16x32_bf16 v[92:95], v[76:79], v[20:23], v[218:221]
	ds_read_b128 v[96:99], v124 offset:3584
	ds_read_b128 v[100:103], v124 offset:128
	ds_read_b128 v[108:111], v124 offset:7168
	ds_read_b128 v[112:115], v124 offset:7232
	ds_read_b128 v[120:123], v124 offset:10752
	ds_read_b128 v[182:185], v124 offset:7296
	v_mfma_f32_16x16x32_bf16 v[76:79], v[76:79], v[24:27], v[222:225]
	s_mul_i32 s1, s0, 0x2800
	s_waitcnt lgkmcnt(5)
	v_mfma_f32_16x16x32_bf16 v[104:107], v[96:99], v[20:23], v[218:221]
	v_mfma_f32_16x16x32_bf16 v[96:99], v[96:99], v[24:27], v[222:225]
	s_waitcnt lgkmcnt(3)
	v_mfma_f32_16x16x32_bf16 v[116:119], v[108:111], v[20:23], v[218:221]
	v_mfma_f32_16x16x32_bf16 v[108:111], v[108:111], v[24:27], v[222:225]
	s_waitcnt lgkmcnt(1)
	v_mfma_f32_16x16x32_bf16 v[80:83], v[120:123], v[20:23], v[218:221]
	v_mfma_f32_16x16x32_bf16 v[84:87], v[120:123], v[24:27], v[222:225]
	v_mfma_f32_16x16x32_bf16 v[92:95], v[88:91], v[12:15], v[92:95]
	v_mfma_f32_16x16x32_bf16 v[76:79], v[88:91], v[16:19], v[76:79]
	ds_read_b128 v[88:91], v124 offset:3648
	ds_read_b128 v[120:123], v124 offset:3712
	s_waitcnt lgkmcnt(1)
	v_mfma_f32_16x16x32_bf16 v[104:107], v[88:91], v[12:15], v[104:107]
	v_mfma_f32_16x16x32_bf16 v[88:91], v[88:91], v[16:19], v[96:99]
	s_nop 2
	ds_read_b128 v[96:99], v124 offset:10816
	ds_read_b128 v[190:193], v124 offset:10880
	s_waitcnt lgkmcnt(1)
	v_mfma_f32_16x16x32_bf16 v[194:197], v[96:99], v[12:15], v[80:83]
	s_nop 2
	v_mfma_f32_16x16x32_bf16 v[128:131], v[100:103], v[4:7], v[76:79]
	v_add_u32_e32 v82, s1, v176
	s_nop 1
	v_mfma_f32_16x16x32_bf16 v[116:119], v[112:115], v[12:15], v[116:119]
	v_mfma_f32_16x16x32_bf16 v[186:189], v[112:115], v[16:19], v[108:111]
	v_mfma_f32_16x16x32_bf16 v[198:201], v[96:99], v[16:19], v[84:87]
	ds_read_b64_tr_b16 v[124:125], v82 offset:28672
	ds_read_b64_tr_b16 v[112:113], v82 offset:28704
	ds_read_b64_tr_b16 v[108:109], v82 offset:28736
	ds_read_b64_tr_b16 v[96:97], v82 offset:28768
	ds_read_b64_tr_b16 v[126:127], v82 offset:31232
	ds_read_b64_tr_b16 v[114:115], v82 offset:31264
	ds_read_b64_tr_b16 v[110:111], v82 offset:31296
	ds_read_b64_tr_b16 v[98:99], v82 offset:31328
	v_mfma_f32_16x16x32_bf16 v[136:139], v[100:103], v[8:11], v[92:95]
	v_mfma_f32_16x16x32_bf16 v[132:135], v[120:123], v[4:7], v[88:91]
	s_nop 1
	ds_read_b64_tr_b16 v[92:93], v82 offset:33792
	ds_read_b64_tr_b16 v[88:89], v82 offset:33824
	ds_read_b64_tr_b16 v[84:85], v82 offset:33856
	ds_read_b64_tr_b16 v[80:81], v82 offset:33888
	ds_read_b64_tr_b16 v[94:95], v82 offset:36352
	ds_read_b64_tr_b16 v[90:91], v82 offset:36384
	ds_read_b64_tr_b16 v[86:87], v82 offset:36416
	ds_read_b64_tr_b16 v[82:83], v82 offset:36448
	v_mfma_f32_16x16x32_bf16 v[140:143], v[120:123], v[8:11], v[104:107]
	v_mfma_f32_16x16x32_bf16 v[116:119], v[182:185], v[8:11], v[116:119]
	v_mfma_f32_16x16x32_bf16 v[100:103], v[182:185], v[4:7], v[186:189]
	s_waitcnt lgkmcnt(14)
	v_mfma_f32_16x16x32_bf16 v[120:123], v[190:193], v[8:11], v[194:197]
	v_mfma_f32_16x16x32_bf16 v[104:107], v[190:193], v[4:7], v[198:201]
	s_setprio 0
	v_max3_f32 v181, v136, v137, v138
	v_max3_f32 v183, v128, v129, v130
	v_max3_f32 v184, v131, v132, v133
	v_max3_f32 v181, v181, v139, v140
	v_max3_f32 v183, v183, v134, v135
	v_max3_f32 v181, v181, v141, v142
	v_max3_f32 v182, v143, v116, v117
	v_max3_f32 v184, v184, v100, v101
	v_max3_f32 v182, v182, v118, v119
	v_max3_f32 v184, v184, v102, v103
	v_max3_f32 v181, v181, v120, v121
	v_max3_f32 v182, v182, v122, v123
	v_max3_f32 v183, v183, v104, v105
	v_max3_f32 v184, v184, v106, v107
	v_max_f32_e32 v181, v181, v182
	v_max_f32_e32 v183, v183, v184
	v_max_f32_e32 v184, v181, v183
	v_cmp_lt_f32_e32 vcc, s36, v184
	s_cbranch_vccz .LBB0_1378
	v_mov_b32_e32 v182, v181
	v_mov_b32_e32 v184, v183
	s_nop 1
	v_permlane16_swap_b32_e32 v181, v182
	v_permlane16_swap_b32_e32 v183, v184
	v_max_f32_e32 v181, v181, v182
	v_max_f32_e32 v183, v183, v184
	v_mov_b32_e32 v182, v181
	v_mov_b32_e32 v184, v183
	s_nop 1
	v_permlane32_swap_b32_e32 v181, v182
	v_permlane32_swap_b32_e32 v183, v184
	v_max_f32_e32 v182, v181, v182
	v_max_f32_e32 v181, v183, v184
	v_max_f32_e32 v182, v182, v182
	v_max_f32_e32 v183, 0, v182
	v_exp_f32_e64 v182, -v183
	v_max_f32_e32 v181, v181, v181
	v_sub_f32_e32 v136, v136, v183
	v_sub_f32_e32 v137, v137, v183
	v_pk_mul_f32 v[70:71], v[70:71], v[182:183] op_sel_hi:[1,0]
	v_pk_mul_f32 v[68:69], v[68:69], v[182:183] op_sel_hi:[1,0]
	v_pk_mul_f32 v[62:63], v[62:63], v[182:183] op_sel_hi:[1,0]
	v_pk_mul_f32 v[60:61], v[60:61], v[182:183] op_sel_hi:[1,0]
	v_pk_mul_f32 v[54:55], v[54:55], v[182:183] op_sel_hi:[1,0]
	v_pk_mul_f32 v[52:53], v[52:53], v[182:183] op_sel_hi:[1,0]
	v_pk_mul_f32 v[46:47], v[46:47], v[182:183] op_sel_hi:[1,0]
	v_pk_mul_f32 v[44:45], v[44:45], v[182:183] op_sel_hi:[1,0]
	v_pk_mul_f32 v[38:39], v[38:39], v[182:183] op_sel_hi:[1,0]
	v_pk_mul_f32 v[36:37], v[36:37], v[182:183] op_sel_hi:[1,0]
	v_max_f32_e32 v182, 0, v181
	v_exp_f32_e64 v184, -v182
	v_sub_f32_e32 v138, v138, v183
	v_sub_f32_e32 v139, v139, v183
	v_sub_f32_e32 v140, v140, v183
	v_sub_f32_e32 v141, v141, v183
	v_sub_f32_e32 v142, v142, v183
	v_sub_f32_e32 v143, v143, v183
	v_sub_f32_e32 v116, v116, v183
	v_sub_f32_e32 v117, v117, v183
	v_sub_f32_e32 v118, v118, v183
	v_sub_f32_e32 v119, v119, v183
	v_sub_f32_e32 v120, v120, v183
	v_sub_f32_e32 v121, v121, v183
	v_sub_f32_e32 v122, v122, v183
	v_sub_f32_e32 v123, v123, v183
	v_pk_add_f32 v[158:159], v[158:159], v[182:183]
	v_xor_b32_e32 v218, 0x80000000, v159
	v_xor_b32_e32 v222, 0x80000000, v158
	v_mov_b32_e32 v219, v218
	v_mov_b32_e32 v220, v218
	v_mov_b32_e32 v221, v218
	v_mov_b32_e32 v223, v222
	v_mov_b32_e32 v224, v222
	v_mov_b32_e32 v225, v222
	v_sub_f32_e32 v128, v128, v182
	v_sub_f32_e32 v129, v129, v182
	v_sub_f32_e32 v130, v130, v182
	v_sub_f32_e32 v131, v131, v182
	v_sub_f32_e32 v132, v132, v182
	v_sub_f32_e32 v133, v133, v182
	v_sub_f32_e32 v134, v134, v182
	v_sub_f32_e32 v135, v135, v182
	v_sub_f32_e32 v100, v100, v182
	v_sub_f32_e32 v101, v101, v182
	v_sub_f32_e32 v102, v102, v182
	v_sub_f32_e32 v103, v103, v182
	v_sub_f32_e32 v104, v104, v182
	v_sub_f32_e32 v105, v105, v182
	v_sub_f32_e32 v106, v106, v182
	v_sub_f32_e32 v107, v107, v182
	v_pk_mul_f32 v[66:67], v[66:67], v[184:185] op_sel_hi:[1,0]
	v_pk_mul_f32 v[64:65], v[64:65], v[184:185] op_sel_hi:[1,0]
	v_pk_mul_f32 v[58:59], v[58:59], v[184:185] op_sel_hi:[1,0]
	v_pk_mul_f32 v[56:57], v[56:57], v[184:185] op_sel_hi:[1,0]
	v_pk_mul_f32 v[50:51], v[50:51], v[184:185] op_sel_hi:[1,0]
	v_pk_mul_f32 v[48:49], v[48:49], v[184:185] op_sel_hi:[1,0]
	v_pk_mul_f32 v[42:43], v[42:43], v[184:185] op_sel_hi:[1,0]
	v_pk_mul_f32 v[40:41], v[40:41], v[184:185] op_sel_hi:[1,0]
	v_pk_mul_f32 v[34:35], v[34:35], v[184:185] op_sel_hi:[1,0]
	v_pk_mul_f32 v[32:33], v[32:33], v[184:185] op_sel_hi:[1,0]
.LBB0_1378:
	v_exp_f32_e32 v136, v136
	v_exp_f32_e32 v137, v137
	v_exp_f32_e32 v138, v138
	v_exp_f32_e32 v139, v139
	v_exp_f32_e32 v140, v140
	v_exp_f32_e32 v141, v141
	v_exp_f32_e32 v142, v142
	v_exp_f32_e32 v143, v143
	v_exp_f32_e32 v128, v128
	v_exp_f32_e32 v129, v129
	v_exp_f32_e32 v130, v130
	v_exp_f32_e32 v131, v131
	v_exp_f32_e32 v132, v132
	v_exp_f32_e32 v133, v133
	v_exp_f32_e32 v134, v134
	v_exp_f32_e32 v135, v135
	v_cvt_pk_bf16_f32 v136, v136, v137
	v_cvt_pk_bf16_f32 v137, v138, v139
	v_cvt_pk_bf16_f32 v138, v140, v141
	v_cvt_pk_bf16_f32 v139, v142, v143
	v_cvt_pk_bf16_f32 v128, v128, v129
	v_cvt_pk_bf16_f32 v129, v130, v131
	v_cvt_pk_bf16_f32 v130, v132, v133
	v_cvt_pk_bf16_f32 v131, v134, v135
	s_waitcnt lgkmcnt(0)
	s_setprio 1
	v_mfma_f32_16x16x32_bf16 v[60:63], v[112:115], v[136:139], v[60:63]
	v_exp_f32_e32 v116, v116
	s_xor_b32 s43, s0, 1
	s_mul_i32 s46, s43, 0x3800
	v_mfma_f32_16x16x32_bf16 v[56:59], v[112:115], v[128:131], v[56:59]
	v_exp_f32_e32 v112, v117
	v_exp_f32_e32 v113, v118
	v_exp_f32_e32 v114, v119
	v_exp_f32_e32 v115, v120
	v_exp_f32_e32 v117, v121
	v_mfma_f32_16x16x32_bf16 v[52:55], v[108:111], v[136:139], v[52:55]
	v_exp_f32_e32 v118, v122
	v_mfma_f32_16x16x32_bf16 v[48:51], v[108:111], v[128:131], v[48:51]
	v_cvt_pk_bf16_f32 v108, v116, v112
	v_cvt_pk_bf16_f32 v109, v113, v114
	v_cvt_pk_bf16_f32 v110, v115, v117
	v_exp_f32_e32 v111, v123
	v_mfma_f32_16x16x32_bf16 v[44:47], v[96:99], v[136:139], v[44:47]
	v_cvt_pk_bf16_f32 v111, v118, v111
	v_mfma_f32_16x16x32_bf16 v[40:43], v[96:99], v[128:131], v[40:43]
	v_exp_f32_e32 v96, v100
	v_exp_f32_e32 v97, v101
	v_exp_f32_e32 v98, v102
	v_exp_f32_e32 v99, v103
	v_exp_f32_e32 v100, v104
	v_exp_f32_e32 v101, v105
	v_exp_f32_e32 v102, v106
	v_exp_f32_e32 v103, v107
	v_mfma_f32_16x16x32_bf16 v[68:71], v[124:127], v[136:139], v[68:71]
	v_cvt_pk_bf16_f32 v96, v96, v97
	v_cvt_pk_bf16_f32 v97, v98, v99
	v_cvt_pk_bf16_f32 v98, v100, v101
	v_mfma_f32_16x16x32_bf16 v[64:67], v[124:127], v[128:131], v[64:67]
	v_cvt_pk_bf16_f32 v99, v102, v103
	v_mfma_f32_16x16x32_bf16 v[36:39], v[228:231], v[136:139], v[36:39]
	v_mfma_f32_16x16x32_bf16 v[32:35], v[228:231], v[128:131], v[32:35]
	v_mfma_f32_16x16x32_bf16 v[68:71], v[92:95], v[108:111], v[68:71]
	v_mfma_f32_16x16x32_bf16 v[64:67], v[92:95], v[96:99], v[64:67]
	v_mfma_f32_16x16x32_bf16 v[60:63], v[88:91], v[108:111], v[60:63]
	v_mfma_f32_16x16x32_bf16 v[56:59], v[88:91], v[96:99], v[56:59]
	v_mfma_f32_16x16x32_bf16 v[52:55], v[84:87], v[108:111], v[52:55]
	v_mfma_f32_16x16x32_bf16 v[48:51], v[84:87], v[96:99], v[48:51]
	v_mfma_f32_16x16x32_bf16 v[44:47], v[80:83], v[108:111], v[44:47]
	v_mfma_f32_16x16x32_bf16 v[40:43], v[80:83], v[96:99], v[40:43]
	v_lshlrev_b32_e32 v80, 1, v170
	v_add3_u32 v80, s46, v80, v180
	s_waitcnt vmcnt(1)
	ds_write_b128 v80, v[72:75]
	v_mfma_f32_16x16x32_bf16 v[36:39], v[228:231], v[108:111], v[36:39]
	v_mfma_f32_16x16x32_bf16 v[32:35], v[228:231], v[96:99], v[32:35]
	s_setprio 0
	s_and_saveexec_b64 s[0:1], s[6:7]
	s_cbranch_execz .LBB0_1373
	v_lshlrev_b32_e32 v72, 1, v171
	v_add3_u32 v72, s46, v72, v144
	ds_write_b128 v72, v[28:31]
	s_branch .LBB0_1373
